# XCC-local seam barriers: every wave invalidates L1 after its last load, ahead of the store drain; thread 0 protocol without invalidate; stacked
# baseline (speedup 1.0000x reference)
; __device__ __forceinline__ unsigned xb_ld(unsigned* p)              { return __hip_atomic_load(p, __ATOMIC_RELAXED, __HIP_MEMORY_SCOPE_AGENT); }
; __device__ __forceinline__ unsigned xb_add(unsigned* p, unsigned v) { return __hip_atomic_fetch_add(p, v, __ATOMIC_RELAXED, __HIP_MEMORY_SCOPE_AGENT); }
; #define XB_SPIN(cond, bar) do { unsigned _sp = 0; while (cond) { __builtin_amdgcn_s_sleep(1); \
;     if ((++_sp & 255u) == 0u) { if (xb_ld(&(bar)[XB_TMO])) break; if (_sp > XB_SPIN_CAP) { atomicAdd(&(bar)[XB_TMO], 1u); break; } } } } while (0)
; #define x (arg_in(0))
; __device__ __forceinline__ void xcd_local_barrier(const XcdBarrier& b) {
;     asm volatile("s_waitcnt vmcnt(0)" ::: "memory");
;     __syncthreads();
;     if (threadIdx.x == 0) {
;         unsigned* bar = b.bar;
;         __builtin_amdgcn_s_waitcnt(0);
;         unsigned nloc = b.st[0], nx = b.st[1];
;         if (nloc == 0u) { xcd_barrier_complete(bar, b.x, nloc, nx); b.st[0] = nloc; b.st[1] = nx; }
;         const unsigned old = xb_add(&bar[XB_XSUB2(b.x)], 1u);
;         const unsigned gen = old / nloc;
;         if (old + 1u == (gen + 1u) * nloc) xb_add(&bar[XB_XGEN2(b.x)], 1u);
;         else XB_SPIN(xb_ld(&bar[XB_XGEN2(b.x)]) == gen, bar);
;         __builtin_amdgcn_fence(__ATOMIC_ACQUIRE, "agent");
;         asm volatile("s_waitcnt vmcnt(0)" ::: "memory");
.LBB0_118:
	s_and_b64 vcc, exec, s[36:37]
	s_cbranch_vccz .LBB0_153
	buffer_inv sc1
	s_waitcnt vmcnt(0)
	s_barrier
	s_mov_b64 s[40:41], exec
	v_readlane_b32 s14, v253, 0
	v_readlane_b32 s15, v253, 1
	s_and_b64 s[14:15], s[40:41], s[14:15]
	s_mov_b64 exec, s[14:15]
	s_cbranch_execz .LBB0_152
	v_readlane_b32 s8, v254, 36
	s_waitcnt vmcnt(0) expcnt(0) lgkmcnt(0)
	s_nop 0
	v_mov_b32_e32 v0, s8
	ds_read_b32 v0, v0
	v_readlane_b32 s8, v254, 37
	s_waitcnt lgkmcnt(0)
	v_cmp_ne_u32_e32 vcc, 0, v0
	v_mov_b32_e32 v1, s8
	ds_read_b32 v1, v1
	s_cbranch_vccnz .LBB0_135
	s_mov_b32 s14, 1
	s_branch .LBB0_123

; __device__ __forceinline__ unsigned xb_ld(unsigned* p)              { return __hip_atomic_load(p, __ATOMIC_RELAXED, __HIP_MEMORY_SCOPE_AGENT); }
; __device__ __forceinline__ unsigned xb_add(unsigned* p, unsigned v) { return __hip_atomic_fetch_add(p, v, __ATOMIC_RELAXED, __HIP_MEMORY_SCOPE_AGENT); }
; #define XB_SPIN(cond, bar) do { unsigned _sp = 0; while (cond) { __builtin_amdgcn_s_sleep(1); \
;     if ((++_sp & 255u) == 0u) { if (xb_ld(&(bar)[XB_TMO])) break; if (_sp > XB_SPIN_CAP) { atomicAdd(&(bar)[XB_TMO], 1u); break; } } } } while (0)
; #define x (arg_in(0))
; __device__ __forceinline__ void xcd_local_barrier(const XcdBarrier& b) {
;     asm volatile("s_waitcnt vmcnt(0)" ::: "memory");
;     __syncthreads();
;     if (threadIdx.x == 0) {
;         unsigned* bar = b.bar;
;         __builtin_amdgcn_s_waitcnt(0);
;         unsigned nloc = b.st[0], nx = b.st[1];
;         if (nloc == 0u) { xcd_barrier_complete(bar, b.x, nloc, nx); b.st[0] = nloc; b.st[1] = nx; }
;         const unsigned old = xb_add(&bar[XB_XSUB2(b.x)], 1u);
;         const unsigned gen = old / nloc;
;         if (old + 1u == (gen + 1u) * nloc) xb_add(&bar[XB_XGEN2(b.x)], 1u);
;         else XB_SPIN(xb_ld(&bar[XB_XGEN2(b.x)]) == gen, bar);
;         __builtin_amdgcn_fence(__ATOMIC_ACQUIRE, "agent");
;         asm volatile("s_waitcnt vmcnt(0)" ::: "memory");
.LBB0_248:
	s_and_b64 vcc, exec, s[36:37]
	s_cbranch_vccz .LBB0_283
	buffer_inv sc1
	s_waitcnt vmcnt(0)
	s_waitcnt vmcnt(0)
	s_barrier
	s_mov_b64 s[40:41], exec
	v_readlane_b32 s14, v253, 0
	v_readlane_b32 s15, v253, 1
	s_and_b64 s[14:15], s[40:41], s[14:15]
	s_mov_b64 exec, s[14:15]
	s_cbranch_execz .LBB0_282
	v_readlane_b32 s8, v254, 36
	s_waitcnt vmcnt(0) expcnt(0) lgkmcnt(0)
	s_nop 0
	v_mov_b32_e32 v0, s8
	ds_read_b32 v0, v0
	v_readlane_b32 s8, v254, 37
	s_waitcnt lgkmcnt(0)
	v_cmp_ne_u32_e32 vcc, 0, v0
	v_mov_b32_e32 v1, s8
	ds_read_b32 v1, v1
	s_cbranch_vccnz .LBB0_265
	s_mov_b32 s14, 1
	s_branch .LBB0_253

; __device__ __forceinline__ unsigned xb_ld(unsigned* p)              { return __hip_atomic_load(p, __ATOMIC_RELAXED, __HIP_MEMORY_SCOPE_AGENT); }
; __device__ __forceinline__ unsigned xb_add(unsigned* p, unsigned v) { return __hip_atomic_fetch_add(p, v, __ATOMIC_RELAXED, __HIP_MEMORY_SCOPE_AGENT); }
; #define XB_SPIN(cond, bar) do { unsigned _sp = 0; while (cond) { __builtin_amdgcn_s_sleep(1); \
;     if ((++_sp & 255u) == 0u) { if (xb_ld(&(bar)[XB_TMO])) break; if (_sp > XB_SPIN_CAP) { atomicAdd(&(bar)[XB_TMO], 1u); break; } } } } while (0)
; #define x (arg_in(0))
; __device__ __forceinline__ void xcd_local_barrier(const XcdBarrier& b) {
;     asm volatile("s_waitcnt vmcnt(0)" ::: "memory");
;     __syncthreads();
;     if (threadIdx.x == 0) {
;         unsigned* bar = b.bar;
;         __builtin_amdgcn_s_waitcnt(0);
;         unsigned nloc = b.st[0], nx = b.st[1];
;         if (nloc == 0u) { xcd_barrier_complete(bar, b.x, nloc, nx); b.st[0] = nloc; b.st[1] = nx; }
;         const unsigned old = xb_add(&bar[XB_XSUB2(b.x)], 1u);
;         const unsigned gen = old / nloc;
;         if (old + 1u == (gen + 1u) * nloc) xb_add(&bar[XB_XGEN2(b.x)], 1u);
;         else XB_SPIN(xb_ld(&bar[XB_XGEN2(b.x)]) == gen, bar);
;         __builtin_amdgcn_fence(__ATOMIC_ACQUIRE, "agent");
;         asm volatile("s_waitcnt vmcnt(0)" ::: "memory");
.LBB0_1071:
	buffer_inv sc1
	s_waitcnt vmcnt(0)
	s_waitcnt vmcnt(0)
	s_barrier
	s_mov_b64 s[38:39], exec
	v_readlane_b32 s12, v253, 0
	v_readlane_b32 s13, v253, 1
	s_and_b64 s[12:13], s[38:39], s[12:13]
	s_mov_b64 exec, s[12:13]
	s_cbranch_execnz .LBB0_1072
	s_getpc_b64 s[98:99]
